# MA non-Fourier row-load sites: unpack reads the prefetch registers directly (32 copies + 16 nops per trip removed), on top of v24
# speedup vs baseline: 1.0090x; 1.0090x over previous
; #define GAS __attribute__((address_space(1)))
; __device__ __forceinline__ unsigned pk2(float lo, float hi) { const f32x2_t v = {lo, hi}; return __builtin_bit_cast(unsigned, __builtin_convertvector(v, bf16x2_t)); }
; __device__ __forceinline__ void phase_ma(const Params& p, Frame& F, int l, const bool fd, const float* xin32) {
;     ...
;         for (int r = 0; r < 4; ++r) { const int row = b * S + s0 + r * rstep; float ss = 0.f;
;             if (fd) { const int k = s0 + r * rstep, m = k & 63, qd = k >> 6; int rr; float sg = 1.0f; bool special = false;
;                 if (m >= 1 && m <= 31) { rr = m * 128 + qd; }
;                 else if (m >= 33) { const int kp = S - k; rr = (kp & 63) * 128 + (kp >> 6); sg = -1.0f; }
;                 else if (m == 0) { if (qd <= 63) rr = qd; else if (qd == 64) { rr = 0; special = true; } else { rr = 128 - qd; sg = -1.0f; } }
;                 else { if (qd <= 63) rr = 64 + qd; else { rr = 64 + (127 - qd); sg = -1.0f; } }
;                 const bf16* P = PQ + ((size_t)(b * 4096 + rr)) * 2048;
; #pragma unroll
;                 for (int j = 0; j < 4; ++j) { const int cc = 256 * j + 4 * F.lane; f32x4 y;
;                     if (special) y = *(const f32x4*)(y4096 + b * 1024 + cc); else { const v2u pw = *(const GAS v2u*)(P + cc), qw = *(const GAS v2u*)(P + 1024 + cc);
;                         y.x = bf_lo(pw.x) + sg * bf_lo(qw.x); y.y = bf_hi(pw.x) + sg * bf_hi(qw.x); y.z = bf_lo(pw.y) + sg * bf_lo(qw.y); y.w = bf_hi(pw.y) + sg * bf_hi(qw.y); }
;                     f32x4 xo; if (xin32) xo = *(const GAS f32x4*)(xin32 + (size_t)row * D + cc); else { const v2u xw = *(const GAS v2u*)(xb + (size_t)row * D + cc); xo = (f32x4){bf_lo(xw.x), bf_hi(xw.x), bf_lo(xw.y), bf_hi(xw.y)}; }
;                     const f32x4 xn = xo + G1[j] * y; v2u ow; ow.x = pk2(xn.x, xn.y); ow.y = pk2(xn.z, xn.w); *(GAS v2u*)(xb + (size_t)row * D + cc) = ow;
;                     h[r][j] = (f32x4){bf_lo(ow.x), bf_hi(ow.x), bf_lo(ow.y), bf_hi(ow.y)}; } }
; #pragma unroll
;             for (int j = 0; j < 4; ++j) { if (!fd) { const v2u xw = *(const GAS v2u*)(xb + (size_t)row * D + 256 * j + 4 * F.lane); h[r][j] = (f32x4){bf_lo(xw.x), bf_hi(xw.x), bf_lo(xw.y), bf_hi(xw.y)}; } ss += (h[r][j].x * h[r][j].x + h[r][j].y * h[r][j].y) + (h[r][j].z * h[r][j].z + h[r][j].w * h[r][j].w); }
.LBB0_615:
	s_waitcnt lgkmcnt(0)
	global_load_dwordx2 v[194:195], v[32:33], off
	global_load_dwordx2 v[196:197], v[32:33], off offset:512
	global_load_dwordx2 v[198:199], v[32:33], off offset:1024
	global_load_dwordx2 v[200:201], v[32:33], off offset:1536
	s_add_i32 vcc_lo, s54, s4
	s_lshl_b32 vcc_lo, vcc_lo, 11
	s_mov_b32 vcc_hi, 0
	v_lshl_add_u64 v[226:227], v[52:53], 0, vcc
	global_load_dwordx2 v[202:203], v[226:227], off
	global_load_dwordx2 v[204:205], v[226:227], off offset:512
	global_load_dwordx2 v[206:207], v[226:227], off offset:1024
	global_load_dwordx2 v[208:209], v[226:227], off offset:1536
	s_add_i32 vcc_lo, s53, s4
	s_lshl_b32 vcc_lo, vcc_lo, 11
	s_mov_b32 vcc_hi, 0
	v_lshl_add_u64 v[228:229], v[52:53], 0, vcc
	global_load_dwordx2 v[210:211], v[228:229], off
	global_load_dwordx2 v[212:213], v[228:229], off offset:512
	global_load_dwordx2 v[214:215], v[228:229], off offset:1024
	global_load_dwordx2 v[216:217], v[228:229], off offset:1536
	s_add_i32 vcc_lo, s5, s4
	s_lshl_b32 vcc_lo, vcc_lo, 11
	s_mov_b32 vcc_hi, 0
	v_lshl_add_u64 v[230:231], v[52:53], 0, vcc
	global_load_dwordx2 v[218:219], v[230:231], off
	global_load_dwordx2 v[220:221], v[230:231], off offset:512
	global_load_dwordx2 v[222:223], v[230:231], off offset:1024
	global_load_dwordx2 v[224:225], v[230:231], off offset:1536
	s_waitcnt vmcnt(0)
	v_lshlrev_b32_e32 v78, 16, v194
	v_and_b32_e32 v79, 0xffff0000, v194
	v_lshlrev_b32_e32 v112, 16, v195
	v_and_b32_e32 v113, 0xffff0000, v195
	s_and_b64 vcc, exec, s[48:49]
	s_cbranch_vccz .LBB0_666

; #define GAS __attribute__((address_space(1)))
; __device__ __forceinline__ void phase_ma(const Params& p, Frame& F, int l, const bool fd, const float* xin32) {
;     ...
;             for (int j = 0; j < 4; ++j) { if (!fd) { const v2u xw = *(const GAS v2u*)(xb + (size_t)row * D + 256 * j + 4 * F.lane); h[r][j] = (f32x4){bf_lo(xw.x), bf_hi(xw.x), bf_lo(xw.y), bf_hi(xw.y)}; } ss += (h[r][j].x * h[r][j].x + h[r][j].y * h[r][j].y) + (h[r][j].z * h[r][j].z + h[r][j].w * h[r][j].w); }
.LBB0_617:
	s_waitcnt lgkmcnt(0)
	s_waitcnt vmcnt(0)
	v_lshlrev_b32_e32 v68, 16, v198
	v_and_b32_e32 v69, 0xffff0000, v198
	v_lshlrev_b32_e32 v96, 16, v199
	v_and_b32_e32 v97, 0xffff0000, v199
	s_and_b64 vcc, exec, s[48:49]
	s_cbranch_vccnz .LBB0_669
	s_branch .LBB0_668

; #define GAS __attribute__((address_space(1)))
; __device__ __forceinline__ void phase_ma(const Params& p, Frame& F, int l, const bool fd, const float* xin32) {
;     ...
;             for (int j = 0; j < 4; ++j) { if (!fd) { const v2u xw = *(const GAS v2u*)(xb + (size_t)row * D + 256 * j + 4 * F.lane); h[r][j] = (f32x4){bf_lo(xw.x), bf_hi(xw.x), bf_lo(xw.y), bf_hi(xw.y)}; } ss += (h[r][j].x * h[r][j].x + h[r][j].y * h[r][j].y) + (h[r][j].z * h[r][j].z + h[r][j].w * h[r][j].w); }
.LBB0_666:
	s_waitcnt lgkmcnt(0)
	s_waitcnt vmcnt(0)
	v_lshlrev_b32_e32 v70, 16, v196
	v_and_b32_e32 v71, 0xffff0000, v196
	v_lshlrev_b32_e32 v104, 16, v197
	v_and_b32_e32 v105, 0xffff0000, v197
	s_and_b64 vcc, exec, s[48:49]
	s_cbranch_vccz .LBB0_617

; #define GAS __attribute__((address_space(1)))
; __device__ __forceinline__ void phase_ma(const Params& p, Frame& F, int l, const bool fd, const float* xin32) {
;     ...
;             for (int j = 0; j < 4; ++j) { if (!fd) { const v2u xw = *(const GAS v2u*)(xb + (size_t)row * D + 256 * j + 4 * F.lane); h[r][j] = (f32x4){bf_lo(xw.x), bf_hi(xw.x), bf_lo(xw.y), bf_hi(xw.y)}; } ss += (h[r][j].x * h[r][j].x + h[r][j].y * h[r][j].y) + (h[r][j].z * h[r][j].z + h[r][j].w * h[r][j].w); }
.LBB0_668:
	s_waitcnt vmcnt(0)
	v_lshlrev_b32_e32 v84, 16, v200
	v_and_b32_e32 v85, 0xffff0000, v200
	v_lshlrev_b32_e32 v126, 16, v201
	v_and_b32_e32 v127, 0xffff0000, v201

; #define GAS __attribute__((address_space(1)))
; __device__ __forceinline__ void phase_ma(const Params& p, Frame& F, int l, const bool fd, const float* xin32) {
;     ...
;             for (int j = 0; j < 4; ++j) { if (!fd) { const v2u xw = *(const GAS v2u*)(xb + (size_t)row * D + 256 * j + 4 * F.lane); h[r][j] = (f32x4){bf_lo(xw.x), bf_hi(xw.x), bf_lo(xw.y), bf_hi(xw.y)}; } ss += (h[r][j].x * h[r][j].x + h[r][j].y * h[r][j].y) + (h[r][j].z * h[r][j].z + h[r][j].w * h[r][j].w); }
.LBB0_672:
	s_waitcnt lgkmcnt(0)
	s_waitcnt vmcnt(0)
	v_lshlrev_b32_e32 v76, 16, v202
	v_and_b32_e32 v77, 0xffff0000, v202
	v_lshlrev_b32_e32 v110, 16, v203
	v_and_b32_e32 v111, 0xffff0000, v203
	s_and_b64 vcc, exec, s[48:49]
	s_cbranch_vccz .LBB0_723

; #define GAS __attribute__((address_space(1)))
; __device__ __forceinline__ void phase_ma(const Params& p, Frame& F, int l, const bool fd, const float* xin32) {
;     ...
;             for (int j = 0; j < 4; ++j) { if (!fd) { const v2u xw = *(const GAS v2u*)(xb + (size_t)row * D + 256 * j + 4 * F.lane); h[r][j] = (f32x4){bf_lo(xw.x), bf_hi(xw.x), bf_lo(xw.y), bf_hi(xw.y)}; } ss += (h[r][j].x * h[r][j].x + h[r][j].y * h[r][j].y) + (h[r][j].z * h[r][j].z + h[r][j].w * h[r][j].w); }
.LBB0_674:
	s_waitcnt lgkmcnt(0)
	s_waitcnt vmcnt(0)
	v_lshlrev_b32_e32 v72, 16, v206
	v_and_b32_e32 v73, 0xffff0000, v206
	v_lshlrev_b32_e32 v92, 16, v207
	v_and_b32_e32 v93, 0xffff0000, v207
	s_and_b64 vcc, exec, s[48:49]
	s_cbranch_vccnz .LBB0_726
	s_branch .LBB0_725

; #define GAS __attribute__((address_space(1)))
; __device__ __forceinline__ void phase_ma(const Params& p, Frame& F, int l, const bool fd, const float* xin32) {
;     ...
;             for (int j = 0; j < 4; ++j) { if (!fd) { const v2u xw = *(const GAS v2u*)(xb + (size_t)row * D + 256 * j + 4 * F.lane); h[r][j] = (f32x4){bf_lo(xw.x), bf_hi(xw.x), bf_lo(xw.y), bf_hi(xw.y)}; } ss += (h[r][j].x * h[r][j].x + h[r][j].y * h[r][j].y) + (h[r][j].z * h[r][j].z + h[r][j].w * h[r][j].w); }
.LBB0_723:
	s_waitcnt lgkmcnt(0)
	s_waitcnt vmcnt(0)
	v_lshlrev_b32_e32 v74, 16, v204
	v_and_b32_e32 v75, 0xffff0000, v204
	v_lshlrev_b32_e32 v102, 16, v205
	v_and_b32_e32 v103, 0xffff0000, v205
	s_and_b64 vcc, exec, s[48:49]
	s_cbranch_vccz .LBB0_674

; #define GAS __attribute__((address_space(1)))
; __device__ __forceinline__ void phase_ma(const Params& p, Frame& F, int l, const bool fd, const float* xin32) {
;     ...
;             for (int j = 0; j < 4; ++j) { if (!fd) { const v2u xw = *(const GAS v2u*)(xb + (size_t)row * D + 256 * j + 4 * F.lane); h[r][j] = (f32x4){bf_lo(xw.x), bf_hi(xw.x), bf_lo(xw.y), bf_hi(xw.y)}; } ss += (h[r][j].x * h[r][j].x + h[r][j].y * h[r][j].y) + (h[r][j].z * h[r][j].z + h[r][j].w * h[r][j].w); }
.LBB0_725:
	s_waitcnt vmcnt(0)
	v_lshlrev_b32_e32 v94, 16, v208
	v_and_b32_e32 v95, 0xffff0000, v208
	v_lshlrev_b32_e32 v124, 16, v209
	v_and_b32_e32 v125, 0xffff0000, v209

; #define GAS __attribute__((address_space(1)))
; __device__ __forceinline__ void phase_ma(const Params& p, Frame& F, int l, const bool fd, const float* xin32) {
;     ...
;             for (int j = 0; j < 4; ++j) { if (!fd) { const v2u xw = *(const GAS v2u*)(xb + (size_t)row * D + 256 * j + 4 * F.lane); h[r][j] = (f32x4){bf_lo(xw.x), bf_hi(xw.x), bf_lo(xw.y), bf_hi(xw.y)}; } ss += (h[r][j].x * h[r][j].x + h[r][j].y * h[r][j].y) + (h[r][j].z * h[r][j].z + h[r][j].w * h[r][j].w); }
.LBB0_729:
	s_waitcnt lgkmcnt(0)
	s_waitcnt vmcnt(0)
	v_lshlrev_b32_e32 v86, 16, v210
	v_and_b32_e32 v87, 0xffff0000, v210
	v_lshlrev_b32_e32 v116, 16, v211
	v_and_b32_e32 v117, 0xffff0000, v211
	s_and_b64 vcc, exec, s[48:49]
	s_cbranch_vccz .LBB0_780

; #define GAS __attribute__((address_space(1)))
; __device__ __forceinline__ void phase_ma(const Params& p, Frame& F, int l, const bool fd, const float* xin32) {
;     ...
;             for (int j = 0; j < 4; ++j) { if (!fd) { const v2u xw = *(const GAS v2u*)(xb + (size_t)row * D + 256 * j + 4 * F.lane); h[r][j] = (f32x4){bf_lo(xw.x), bf_hi(xw.x), bf_lo(xw.y), bf_hi(xw.y)}; } ss += (h[r][j].x * h[r][j].x + h[r][j].y * h[r][j].y) + (h[r][j].z * h[r][j].z + h[r][j].w * h[r][j].w); }
.LBB0_731:
	s_waitcnt lgkmcnt(0)
	s_waitcnt vmcnt(0)
	v_lshlrev_b32_e32 v80, 16, v214
	v_and_b32_e32 v81, 0xffff0000, v214
	v_lshlrev_b32_e32 v100, 16, v215
	v_and_b32_e32 v101, 0xffff0000, v215
	s_and_b64 vcc, exec, s[48:49]
	s_cbranch_vccnz .LBB0_783
	s_branch .LBB0_782

; #define GAS __attribute__((address_space(1)))
; __device__ __forceinline__ void phase_ma(const Params& p, Frame& F, int l, const bool fd, const float* xin32) {
;     ...
;             for (int j = 0; j < 4; ++j) { if (!fd) { const v2u xw = *(const GAS v2u*)(xb + (size_t)row * D + 256 * j + 4 * F.lane); h[r][j] = (f32x4){bf_lo(xw.x), bf_hi(xw.x), bf_lo(xw.y), bf_hi(xw.y)}; } ss += (h[r][j].x * h[r][j].x + h[r][j].y * h[r][j].y) + (h[r][j].z * h[r][j].z + h[r][j].w * h[r][j].w); }
.LBB0_780:
	s_waitcnt lgkmcnt(0)
	s_waitcnt vmcnt(0)
	v_lshlrev_b32_e32 v82, 16, v212
	v_and_b32_e32 v83, 0xffff0000, v212
	v_lshlrev_b32_e32 v106, 16, v213
	v_and_b32_e32 v107, 0xffff0000, v213
	s_and_b64 vcc, exec, s[48:49]
	s_cbranch_vccz .LBB0_731

; #define GAS __attribute__((address_space(1)))
; __device__ __forceinline__ void phase_ma(const Params& p, Frame& F, int l, const bool fd, const float* xin32) {
;     ...
;             for (int j = 0; j < 4; ++j) { if (!fd) { const v2u xw = *(const GAS v2u*)(xb + (size_t)row * D + 256 * j + 4 * F.lane); h[r][j] = (f32x4){bf_lo(xw.x), bf_hi(xw.x), bf_lo(xw.y), bf_hi(xw.y)}; } ss += (h[r][j].x * h[r][j].x + h[r][j].y * h[r][j].y) + (h[r][j].z * h[r][j].z + h[r][j].w * h[r][j].w); }
.LBB0_782:
	s_waitcnt vmcnt(0)
	v_lshlrev_b32_e32 v114, 16, v216
	v_and_b32_e32 v115, 0xffff0000, v216
	v_lshlrev_b32_e32 v128, 16, v217
	v_and_b32_e32 v129, 0xffff0000, v217

; #define GAS __attribute__((address_space(1)))
; __device__ __forceinline__ void phase_ma(const Params& p, Frame& F, int l, const bool fd, const float* xin32) {
;     ...
;             for (int j = 0; j < 4; ++j) { if (!fd) { const v2u xw = *(const GAS v2u*)(xb + (size_t)row * D + 256 * j + 4 * F.lane); h[r][j] = (f32x4){bf_lo(xw.x), bf_hi(xw.x), bf_lo(xw.y), bf_hi(xw.y)}; } ss += (h[r][j].x * h[r][j].x + h[r][j].y * h[r][j].y) + (h[r][j].z * h[r][j].z + h[r][j].w * h[r][j].w); }
.LBB0_786:
	s_waitcnt lgkmcnt(0)
	s_waitcnt vmcnt(0)
	v_lshlrev_b32_e32 v98, 16, v218
	v_and_b32_e32 v99, 0xffff0000, v218
	v_lshlrev_b32_e32 v120, 16, v219
	v_and_b32_e32 v121, 0xffff0000, v219
	s_and_b64 vcc, exec, s[48:49]
	s_cbranch_vccz .LBB0_837

; #define GAS __attribute__((address_space(1)))
; __device__ __forceinline__ void phase_ma(const Params& p, Frame& F, int l, const bool fd, const float* xin32) {
;     ...
;             for (int j = 0; j < 4; ++j) { if (!fd) { const v2u xw = *(const GAS v2u*)(xb + (size_t)row * D + 256 * j + 4 * F.lane); h[r][j] = (f32x4){bf_lo(xw.x), bf_hi(xw.x), bf_lo(xw.y), bf_hi(xw.y)}; } ss += (h[r][j].x * h[r][j].x + h[r][j].y * h[r][j].y) + (h[r][j].z * h[r][j].z + h[r][j].w * h[r][j].w); }
.LBB0_788:
	s_waitcnt lgkmcnt(0)
	s_waitcnt vmcnt(0)
	v_lshlrev_b32_e32 v88, 16, v222
	v_and_b32_e32 v89, 0xffff0000, v222
	v_lshlrev_b32_e32 v108, 16, v223
	v_and_b32_e32 v109, 0xffff0000, v223
	s_and_b64 vcc, exec, s[48:49]
	s_cbranch_vccz .LBB0_839
	s_branch .LBB0_840

; #define GAS __attribute__((address_space(1)))
; __device__ __forceinline__ void phase_ma(const Params& p, Frame& F, int l, const bool fd, const float* xin32) {
;     ...
;             for (int j = 0; j < 4; ++j) { if (!fd) { const v2u xw = *(const GAS v2u*)(xb + (size_t)row * D + 256 * j + 4 * F.lane); h[r][j] = (f32x4){bf_lo(xw.x), bf_hi(xw.x), bf_lo(xw.y), bf_hi(xw.y)}; } ss += (h[r][j].x * h[r][j].x + h[r][j].y * h[r][j].y) + (h[r][j].z * h[r][j].z + h[r][j].w * h[r][j].w); }
.LBB0_837:
	s_waitcnt lgkmcnt(0)
	s_waitcnt vmcnt(0)
	v_lshlrev_b32_e32 v90, 16, v220
	v_and_b32_e32 v91, 0xffff0000, v220
	v_lshlrev_b32_e32 v118, 16, v221
	v_and_b32_e32 v119, 0xffff0000, v221
	s_and_b64 vcc, exec, s[48:49]
	s_cbranch_vccz .LBB0_788

; #define GAS __attribute__((address_space(1)))
; __device__ __forceinline__ void phase_ma(const Params& p, Frame& F, int l, const bool fd, const float* xin32) {
;     ...
;             for (int j = 0; j < 4; ++j) { if (!fd) { const v2u xw = *(const GAS v2u*)(xb + (size_t)row * D + 256 * j + 4 * F.lane); h[r][j] = (f32x4){bf_lo(xw.x), bf_hi(xw.x), bf_lo(xw.y), bf_hi(xw.y)}; } ss += (h[r][j].x * h[r][j].x + h[r][j].y * h[r][j].y) + (h[r][j].z * h[r][j].z + h[r][j].w * h[r][j].w); }
.LBB0_839:
	s_waitcnt vmcnt(0)
	v_lshlrev_b32_e32 v122, 16, v224
	v_and_b32_e32 v123, 0xffff0000, v224
	v_lshlrev_b32_e32 v130, 16, v225
	v_and_b32_e32 v131, 0xffff0000, v225
